# rmsnorm row loops: counted vmcnt waits in front of the first use of each of the 16 row loads instead of one vmcnt(0)
# baseline (speedup 1.0000x reference)
; __device__ __forceinline__ void rmsnorm_rows(const float* X, const float* g, bf16* H, float* Of, int gw, int ngw, int lane) {
;     f32x4 gv[4];
; #pragma unroll
;     for (int j = 0; j < 4; ++j) gv[j] = *(const f32x4*)(g + 4 * lane + 256 * j);
;     for (int row0 = 4 * gw; row0 < T; row0 += 4 * ngw) {
;         f32x4 v[4][4]; float s[4] = {0.f, 0.f, 0.f, 0.f};
; #pragma unroll
;         for (int r = 0; r < 4; ++r)
; #pragma unroll
;             for (int j = 0; j < 4; ++j) v[r][j] = *(const f32x4*)(X + (size_t)(row0 + r) * D + 4 * lane + 256 * j);
;         __builtin_amdgcn_sched_barrier(0);
; #pragma unroll
;         for (int r = 0; r < 4; ++r)
; #pragma unroll
;             for (int j = 0; j < 4; ++j) s[r] += (v[r][j].x * v[r][j].x + v[r][j].y * v[r][j].y) + (v[r][j].z * v[r][j].z + v[r][j].w * v[r][j].w);
.LBB0_790:
	s_cmpk_gt_i32 s81, 0xfff
	s_cbranch_scc1 .LBB0_793
	s_load_dwordx2 s[0:1], s[30:31], 0x8
	v_readlane_b32 s2, v254, 61
	v_readlane_b32 s3, v254, 62
	s_mov_b32 s4, s2
	s_ashr_i32 s5, s2, 31
	v_writelane_b32 v254, s2, 61
	v_lshlrev_b32_e32 v152, 4, v228
	s_nop 0
	v_writelane_b32 v254, s3, 62
	s_lshl_b64 s[2:3], s[4:5], 12
	s_waitcnt lgkmcnt(0)
	s_add_u32 s0, s0, s2
	s_addc_u32 s1, s1, s3
	v_lshl_add_u64 v[0:1], s[0:1], 0, v[152:153]
	s_mov_b64 s[0:1], 0x1000
	v_add_co_u32_e32 v8, vcc, 0x1000, v0
	v_lshl_add_u64 v[12:13], v[0:1], 0, s[0:1]
	s_nop 0
	v_addc_co_u32_e32 v9, vcc, 0, v1, vcc
	global_load_dwordx4 v[0:3], v[12:13], off offset:1024
	global_load_dwordx4 v[4:7], v[12:13], off offset:2048
	s_nop 0
	global_load_dwordx4 v[8:11], v[8:9], off
	s_nop 0
	global_load_dwordx4 v[12:15], v[12:13], off offset:3072
	s_lshl_b32 s4, s81, 2
	s_ashr_i32 s5, s4, 31
	s_lshl_b64 s[0:1], s[4:5], 11
	v_lshl_or_b32 v80, v228, 3, s0
	v_mov_b32_e32 v81, s1
	s_lshl_b64 s[0:1], s[4:5], 12
	v_lshl_or_b32 v82, v228, 4, s0
	v_mov_b32_e32 v83, s1
.LBB0_792:
	v_lshl_add_u64 v[16:17], s[72:73], 0, v[82:83]
	v_add_co_u32_e32 v18, vcc, 0x1080000, v16
	s_nop 1
	v_addc_co_u32_e32 v19, vcc, 0, v17, vcc
	global_load_dwordx4 v[76:79], v[18:19], off
	global_load_dwordx4 v[72:75], v[18:19], off offset:1024
	global_load_dwordx4 v[68:71], v[18:19], off offset:2048
	global_load_dwordx4 v[64:67], v[18:19], off offset:3072
	v_add_co_u32_e32 v18, vcc, 0x1081000, v16
	s_nop 1
	v_addc_co_u32_e32 v19, vcc, 0, v17, vcc
	global_load_dwordx4 v[60:63], v[18:19], off
	global_load_dwordx4 v[56:59], v[18:19], off offset:1024
	global_load_dwordx4 v[52:55], v[18:19], off offset:2048
	global_load_dwordx4 v[48:51], v[18:19], off offset:3072
	v_add_co_u32_e32 v18, vcc, 0x1082000, v16
	s_nop 1
	v_addc_co_u32_e32 v19, vcc, 0, v17, vcc
	v_add_co_u32_e32 v16, vcc, 0x1083000, v16
	global_load_dwordx4 v[44:47], v[18:19], off
	global_load_dwordx4 v[40:43], v[18:19], off offset:1024
	global_load_dwordx4 v[36:39], v[18:19], off offset:2048
	global_load_dwordx4 v[32:35], v[18:19], off offset:3072
	v_addc_co_u32_e32 v17, vcc, 0, v17, vcc
	global_load_dwordx4 v[28:31], v[16:17], off
	global_load_dwordx4 v[24:27], v[16:17], off offset:1024
	global_load_dwordx4 v[20:23], v[16:17], off offset:2048
	s_nop 0
	global_load_dwordx4 v[16:19], v[16:17], off offset:3072
	s_waitcnt vmcnt(15)
	v_pk_mul_f32 v[84:85], v[78:79], v[78:79]
	v_pk_mul_f32 v[86:87], v[76:77], v[76:77]
	s_add_i32 s4, s4, s64
	v_pk_mov_b32 v[88:89], v[86:87], v[84:85] op_sel:[1,0]
	v_mov_b32_e32 v87, v85
	v_pk_add_f32 v[84:85], v[88:89], v[86:87]
	s_waitcnt vmcnt(14)
	v_pk_mul_f32 v[86:87], v[74:75], v[74:75]
	v_pk_mul_f32 v[88:89], v[72:73], v[72:73]
	v_pk_add_f32 v[84:85], v[84:85], v[84:85] op_sel:[0,1] op_sel_hi:[1,0]
	v_pk_mov_b32 v[90:91], v[88:89], v[86:87] op_sel:[1,0]
	v_mov_b32_e32 v89, v87
	v_pk_add_f32 v[86:87], v[90:91], v[88:89]
	s_waitcnt vmcnt(12)
	v_mul_f32_e32 v88, v64, v64
	v_mul_f32_e32 v89, v65, v65
	v_pk_add_f32 v[86:87], v[86:87], v[86:87] op_sel:[0,1] op_sel_hi:[1,0]
	v_mov_b32_e32 v85, v88
	v_mov_b32_e32 v87, v89
	v_pk_add_f32 v[84:85], v[84:85], v[86:87]
	v_mul_f32_e32 v86, v69, v69
	v_mul_f32_e32 v88, v71, v71
	v_mul_f32_e32 v90, v66, v66
	v_mul_f32_e32 v91, v67, v67
	v_pk_fma_f32 v[86:87], v[68:69], v[68:69], v[86:87] op_sel_hi:[1,1,0]
	v_pk_fma_f32 v[88:89], v[70:71], v[70:71], v[88:89] op_sel_hi:[1,1,0]
	v_mov_b32_e32 v87, v90
	v_mov_b32_e32 v89, v91
	v_pk_add_f32 v[86:87], v[86:87], v[88:89]
	v_lshl_add_u64 v[82:83], v[82:83], 0, s[84:85]
	v_pk_add_f32 v[84:85], v[84:85], v[86:87]
	s_waitcnt vmcnt(11)
	v_pk_mul_f32 v[86:87], v[60:61], v[60:61]
	v_add_f32_e32 v92, v84, v85
	v_pk_mul_f32 v[84:85], v[62:63], v[62:63]
	s_cmpk_gt_i32 s4, 0x3fff
	v_pk_mov_b32 v[88:89], v[86:87], v[84:85] op_sel:[1,0]
	v_mov_b32_e32 v87, v85
	v_pk_add_f32 v[84:85], v[88:89], v[86:87]
	s_waitcnt vmcnt(10)
	v_pk_mul_f32 v[86:87], v[58:59], v[58:59]
	v_pk_mul_f32 v[88:89], v[56:57], v[56:57]
	v_pk_add_f32 v[84:85], v[84:85], v[84:85] op_sel:[0,1] op_sel_hi:[1,0]
	v_pk_mov_b32 v[90:91], v[88:89], v[86:87] op_sel:[1,0]
	v_mov_b32_e32 v89, v87
	v_pk_add_f32 v[86:87], v[90:91], v[88:89]
	s_waitcnt vmcnt(8)
	v_mul_f32_e32 v88, v48, v48
	v_mul_f32_e32 v89, v49, v49
	v_pk_add_f32 v[86:87], v[86:87], v[86:87] op_sel:[0,1] op_sel_hi:[1,0]
	v_mov_b32_e32 v85, v88
	v_mov_b32_e32 v87, v89
	v_pk_add_f32 v[84:85], v[84:85], v[86:87]
	v_mul_f32_e32 v86, v53, v53
	v_mul_f32_e32 v88, v55, v55
	v_mul_f32_e32 v90, v50, v50
	v_mul_f32_e32 v91, v51, v51
	v_pk_fma_f32 v[86:87], v[52:53], v[52:53], v[86:87] op_sel_hi:[1,1,0]
	v_pk_fma_f32 v[88:89], v[54:55], v[54:55], v[88:89] op_sel_hi:[1,1,0]
	v_mov_b32_e32 v87, v90
	v_mov_b32_e32 v89, v91
	v_pk_add_f32 v[86:87], v[86:87], v[88:89]
	s_nop 0
	v_pk_add_f32 v[84:85], v[84:85], v[86:87]
	s_waitcnt vmcnt(7)
	v_pk_mul_f32 v[86:87], v[44:45], v[44:45]
	v_add_f32_e32 v93, v84, v85
	v_pk_mul_f32 v[84:85], v[46:47], v[46:47]
	s_nop 0
	v_pk_mov_b32 v[88:89], v[86:87], v[84:85] op_sel:[1,0]
	v_mov_b32_e32 v87, v85
	v_pk_add_f32 v[84:85], v[88:89], v[86:87]
	s_waitcnt vmcnt(6)
	v_pk_mul_f32 v[86:87], v[42:43], v[42:43]
	v_pk_mul_f32 v[88:89], v[40:41], v[40:41]
	v_pk_add_f32 v[84:85], v[84:85], v[84:85] op_sel:[0,1] op_sel_hi:[1,0]
	v_pk_mov_b32 v[90:91], v[88:89], v[86:87] op_sel:[1,0]
	v_mov_b32_e32 v89, v87
	v_pk_add_f32 v[86:87], v[90:91], v[88:89]
	s_waitcnt vmcnt(4)
; __device__ __forceinline__ unsigned pk2(float lo, float hi) { return f2bf(lo) | (f2bf(hi) << 16); }
; __device__ __forceinline__ float frsq(float x) { return __builtin_amdgcn_rsqf(x); }
; __device__ __forceinline__ void rmsnorm_rows(const float* X, const float* g, bf16* H, float* Of, int gw, int ngw, int lane) {
;     ...
;             for (int j = 0; j < 4; ++j) s[r] += (v[r][j].x * v[r][j].x + v[r][j].y * v[r][j].y) + (v[r][j].z * v[r][j].z + v[r][j].w * v[r][j].w);
; #pragma unroll
;         for (int r = 0; r < 4; ++r) {
;             const float rstd = frsq(wave_sum(s[r]) * (1.f / D) + 1e-6f);
; #pragma unroll
;             for (int j = 0; j < 4; ++j) {
;                 const f32x4 o = v[r][j] * rstd * gv[j];
;                 if (Of) *(f32x4*)(Of + (size_t)(row0 + r) * D + 4 * lane + 256 * j) = o;
;                 else { u32x2 w; w.x = pk2(o.x, o.y); w.y = pk2(o.z, o.w); *(u32x2*)(H + (size_t)(row0 + r) * D + 4 * lane + 256 * j) = w; }
	v_mul_f32_e32 v88, v32, v32
	v_mul_f32_e32 v89, v33, v33
	v_pk_add_f32 v[86:87], v[86:87], v[86:87] op_sel:[0,1] op_sel_hi:[1,0]
	v_mov_b32_e32 v85, v88
	v_mov_b32_e32 v87, v89
	v_pk_add_f32 v[84:85], v[84:85], v[86:87]
	v_mul_f32_e32 v86, v37, v37
	v_mul_f32_e32 v88, v39, v39
	v_mul_f32_e32 v90, v34, v34
	v_mul_f32_e32 v91, v35, v35
	v_pk_fma_f32 v[86:87], v[36:37], v[36:37], v[86:87] op_sel_hi:[1,1,0]
	v_pk_fma_f32 v[88:89], v[38:39], v[38:39], v[88:89] op_sel_hi:[1,1,0]
	v_mov_b32_e32 v87, v90
	v_mov_b32_e32 v89, v91
	v_pk_add_f32 v[86:87], v[86:87], v[88:89]
	s_nop 0
	v_pk_add_f32 v[84:85], v[84:85], v[86:87]
	s_waitcnt vmcnt(3)
	v_pk_mul_f32 v[86:87], v[28:29], v[28:29]
	v_add_f32_e32 v94, v84, v85
	v_pk_mul_f32 v[84:85], v[30:31], v[30:31]
	s_nop 0
	v_pk_mov_b32 v[88:89], v[86:87], v[84:85] op_sel:[1,0]
	v_mov_b32_e32 v87, v85
	v_pk_add_f32 v[84:85], v[88:89], v[86:87]
	s_waitcnt vmcnt(2)
	v_pk_mul_f32 v[86:87], v[26:27], v[26:27]
	v_pk_mul_f32 v[88:89], v[24:25], v[24:25]
	v_pk_add_f32 v[84:85], v[84:85], v[84:85] op_sel:[0,1] op_sel_hi:[1,0]
	v_pk_mov_b32 v[90:91], v[88:89], v[86:87] op_sel:[1,0]
	v_mov_b32_e32 v89, v87
	v_pk_add_f32 v[86:87], v[90:91], v[88:89]
	s_waitcnt vmcnt(0)
	v_mul_f32_e32 v88, v16, v16
	v_mul_f32_e32 v89, v17, v17
	v_pk_add_f32 v[86:87], v[86:87], v[86:87] op_sel:[0,1] op_sel_hi:[1,0]
	v_mov_b32_e32 v85, v88
	v_mov_b32_e32 v87, v89
	v_pk_add_f32 v[84:85], v[84:85], v[86:87]
	v_mul_f32_e32 v86, v21, v21
	v_mul_f32_e32 v88, v23, v23
	v_mul_f32_e32 v90, v18, v18
	v_mul_f32_e32 v91, v19, v19
	v_pk_fma_f32 v[86:87], v[20:21], v[20:21], v[86:87] op_sel_hi:[1,1,0]
	v_pk_fma_f32 v[88:89], v[22:23], v[22:23], v[88:89] op_sel_hi:[1,1,0]
	v_mov_b32_e32 v87, v90
	v_mov_b32_e32 v89, v91
	v_pk_add_f32 v[86:87], v[86:87], v[88:89]
	s_nop 0
	v_pk_add_f32 v[84:85], v[84:85], v[86:87]
	v_lshl_add_u64 v[86:87], s[72:73], 0, v[80:81]
	v_add_f32_e32 v90, v84, v85
	v_add_f32_dpp v84, v92, v92 quad_perm:[1,0,3,2] row_mask:0xf bank_mask:0xf bound_ctrl:1
	v_lshl_add_u64 v[80:81], v[80:81], 0, s[56:57]
	s_nop 0
	v_add_f32_dpp v84, v84, v84 quad_perm:[2,3,0,1] row_mask:0xf bank_mask:0xf bound_ctrl:1
	s_nop 1
	v_add_f32_dpp v84, v84, v84 row_half_mirror row_mask:0xf bank_mask:0xf bound_ctrl:1
	s_nop 1
	v_add_f32_dpp v84, v84, v84 row_mirror row_mask:0xf bank_mask:0xf bound_ctrl:1
	s_nop 0
	v_readlane_b32 s2, v84, 16
	v_readlane_b32 s3, v84, 48
	v_readlane_b32 s0, v84, 0
	v_readlane_b32 s1, v84, 32
	v_mov_b32_e32 v84, s2
	v_mov_b32_e32 v85, s3
	v_pk_add_f32 v[84:85], s[0:1], v[84:85]
	s_nop 0
	v_add_f32_e32 v84, v84, v85
	v_fmamk_f32 v84, v84, 0x3a800000, v220
	v_rsq_f32_e32 v84, v84
	s_nop 0
	v_pk_mul_f32 v[76:77], v[76:77], v[84:85] op_sel_hi:[1,0]
	s_nop 0
	v_pk_mul_f32 v[76:77], v[8:9], v[76:77]
	v_pk_mul_f32 v[78:79], v[78:79], v[84:85] op_sel_hi:[1,0]
	v_bfe_u32 v85, v76, 16, 1
	v_add3_u32 v76, v76, v85, s33
	v_bfe_u32 v85, v77, 16, 1
	v_pk_mul_f32 v[72:73], v[72:73], v[84:85] op_sel_hi:[1,0]
	v_add3_u32 v77, v77, v85, s33
	v_pk_mul_f32 v[72:73], v[0:1], v[72:73]
	v_pk_mul_f32 v[74:75], v[74:75], v[84:85] op_sel_hi:[1,0]
	v_bfe_u32 v85, v72, 16, 1
	v_add3_u32 v72, v72, v85, s33
	v_bfe_u32 v85, v73, 16, 1
	v_pk_mul_f32 v[74:75], v[2:3], v[74:75]
	v_lshrrev_b32_e32 v72, 16, v72
	v_add3_u32 v73, v73, v85, s33
	v_pk_mul_f32 v[78:79], v[10:11], v[78:79]
	v_lshrrev_b32_e32 v76, 16, v76
	v_and_or_b32 v72, v73, s87, v72
	v_bfe_u32 v73, v74, 16, 1
	v_and_or_b32 v88, v77, s87, v76
	v_bfe_u32 v76, v78, 16, 1
	v_add3_u32 v73, v74, v73, s33
	v_bfe_u32 v74, v75, 16, 1
	v_add3_u32 v76, v78, v76, s33
	v_bfe_u32 v77, v79, 16, 1
	v_add_co_u32_e32 v78, vcc, s89, v86
	v_lshrrev_b32_e32 v73, 16, v73
	v_add3_u32 v74, v75, v74, s33
	v_pk_mul_f32 v[68:69], v[68:69], v[84:85] op_sel_hi:[1,0]
	v_add3_u32 v77, v79, v77, s33
	v_addc_co_u32_e32 v79, vcc, 0, v87, vcc
	v_and_or_b32 v73, v74, s87, v73
	v_pk_mul_f32 v[68:69], v[4:5], v[68:69]
	global_store_dwordx2 v[78:79], v[72:73], off offset:512
	v_bfe_u32 v72, v68, 16, 1
	v_pk_mul_f32 v[70:71], v[70:71], v[84:85] op_sel_hi:[1,0]
	v_add3_u32 v68, v68, v72, s33
	v_bfe_u32 v72, v69, 16, 1
	v_pk_mul_f32 v[70:71], v[6:7], v[70:71]
	v_lshrrev_b32_e32 v68, 16, v68
	v_add3_u32 v69, v69, v72, s33
	v_and_or_b32 v68, v69, s87, v68
	v_bfe_u32 v69, v70, 16, 1
	v_add3_u32 v69, v70, v69, s33
	v_bfe_u32 v70, v71, 16, 1
	v_lshrrev_b32_e32 v69, 16, v69
	v_add3_u32 v70, v71, v70, s33
	v_pk_mul_f32 v[64:65], v[64:65], v[84:85] op_sel_hi:[1,0]
	v_and_or_b32 v69, v70, s87, v69
	v_pk_mul_f32 v[64:65], v[12:13], v[64:65]
	global_store_dwordx2 v[78:79], v[68:69], off offset:1024
	v_bfe_u32 v68, v64, 16, 1
	v_pk_mul_f32 v[66:67], v[66:67], v[84:85] op_sel_hi:[1,0]
	v_add3_u32 v64, v64, v68, s33
	v_bfe_u32 v68, v65, 16, 1
	v_pk_mul_f32 v[66:67], v[14:15], v[66:67]
	v_lshrrev_b32_e32 v64, 16, v64
	v_add3_u32 v65, v65, v68, s33
	v_and_or_b32 v64, v65, s87, v64
	v_bfe_u32 v65, v66, 16, 1
	v_add3_u32 v65, v66, v65, s33
	v_bfe_u32 v66, v67, 16, 1
	v_lshrrev_b32_e32 v65, 16, v65
	v_add3_u32 v66, v67, v66, s33
	v_and_or_b32 v65, v66, s87, v65
	global_store_dwordx2 v[78:79], v[64:65], off offset:1536
	v_add_f32_dpp v64, v93, v93 quad_perm:[1,0,3,2] row_mask:0xf bank_mask:0xf bound_ctrl:1
	v_lshrrev_b32_e32 v76, 16, v76
	v_and_or_b32 v89, v77, s87, v76
	v_add_f32_dpp v64, v64, v64 quad_perm:[2,3,0,1] row_mask:0xf bank_mask:0xf bound_ctrl:1
	v_add_co_u32_e32 v76, vcc, s92, v86
	s_nop 0
	v_add_f32_dpp v64, v64, v64 row_half_mirror row_mask:0xf bank_mask:0xf bound_ctrl:1
	v_addc_co_u32_e32 v77, vcc, 0, v87, vcc
	s_nop 0
	v_add_f32_dpp v64, v64, v64 row_mirror row_mask:0xf bank_mask:0xf bound_ctrl:1
	global_store_dwordx2 v[76:77], v[88:89], off offset:-4096
; __device__ __forceinline__ unsigned pk2(float lo, float hi) { return f2bf(lo) | (f2bf(hi) << 16); }
; __device__ __forceinline__ float frsq(float x) { return __builtin_amdgcn_rsqf(x); }
; __device__ __forceinline__ void rmsnorm_rows(const float* X, const float* g, bf16* H, float* Of, int gw, int ngw, int lane) {
;     ...
;         for (int r = 0; r < 4; ++r) {
;             const float rstd = frsq(wave_sum(s[r]) * (1.f / D) + 1e-6f);
; #pragma unroll
;             for (int j = 0; j < 4; ++j) {
;                 const f32x4 o = v[r][j] * rstd * gv[j];
;                 if (Of) *(f32x4*)(Of + (size_t)(row0 + r) * D + 4 * lane + 256 * j) = o;
;                 else { u32x2 w; w.x = pk2(o.x, o.y); w.y = pk2(o.z, o.w); *(u32x2*)(H + (size_t)(row0 + r) * D + 4 * lane + 256 * j) = w; }
;             }
	v_readlane_b32 s2, v64, 16
	v_readlane_b32 s3, v64, 48
	v_readlane_b32 s0, v64, 0
	v_readlane_b32 s1, v64, 32
	v_mov_b32_e32 v64, s2
	v_mov_b32_e32 v65, s3
	v_pk_add_f32 v[64:65], s[0:1], v[64:65]
	s_nop 0
	v_add_f32_e32 v64, v64, v65
	v_fmamk_f32 v64, v64, 0x3a800000, v220
	v_rsq_f32_e32 v64, v64
	s_nop 0
	v_pk_mul_f32 v[60:61], v[60:61], v[64:65] op_sel_hi:[1,0]
	s_nop 0
	v_pk_mul_f32 v[60:61], v[8:9], v[60:61]
	v_pk_mul_f32 v[62:63], v[62:63], v[64:65] op_sel_hi:[1,0]
	v_bfe_u32 v65, v60, 16, 1
	v_add3_u32 v60, v60, v65, s33
	v_bfe_u32 v65, v61, 16, 1
	v_pk_mul_f32 v[62:63], v[10:11], v[62:63]
	v_lshrrev_b32_e32 v60, 16, v60
	v_add3_u32 v61, v61, v65, s33
	v_and_or_b32 v60, v61, s87, v60
	v_bfe_u32 v61, v62, 16, 1
	v_add3_u32 v61, v62, v61, s33
	v_bfe_u32 v62, v63, 16, 1
	v_lshrrev_b32_e32 v61, 16, v61
	v_add3_u32 v62, v63, v62, s33
	v_pk_mul_f32 v[56:57], v[56:57], v[64:65] op_sel_hi:[1,0]
	v_and_or_b32 v61, v62, s87, v61
	v_pk_mul_f32 v[56:57], v[0:1], v[56:57]
	global_store_dwordx2 v[78:79], v[60:61], off offset:2048
	v_bfe_u32 v60, v56, 16, 1
	v_pk_mul_f32 v[58:59], v[58:59], v[64:65] op_sel_hi:[1,0]
	v_add3_u32 v56, v56, v60, s33
	v_bfe_u32 v60, v57, 16, 1
	v_pk_mul_f32 v[58:59], v[2:3], v[58:59]
	v_lshrrev_b32_e32 v56, 16, v56
	v_add3_u32 v57, v57, v60, s33
	v_and_or_b32 v56, v57, s87, v56
	v_bfe_u32 v57, v58, 16, 1
	v_add3_u32 v57, v58, v57, s33
	v_bfe_u32 v58, v59, 16, 1
	v_lshrrev_b32_e32 v57, 16, v57
	v_add3_u32 v58, v59, v58, s33
	v_pk_mul_f32 v[52:53], v[52:53], v[64:65] op_sel_hi:[1,0]
	v_and_or_b32 v57, v58, s87, v57
	v_pk_mul_f32 v[52:53], v[4:5], v[52:53]
	global_store_dwordx2 v[78:79], v[56:57], off offset:2560
	v_bfe_u32 v56, v52, 16, 1
	v_pk_mul_f32 v[54:55], v[54:55], v[64:65] op_sel_hi:[1,0]
	v_add3_u32 v52, v52, v56, s33
	v_bfe_u32 v56, v53, 16, 1
	v_pk_mul_f32 v[54:55], v[6:7], v[54:55]
	v_lshrrev_b32_e32 v52, 16, v52
	v_add3_u32 v53, v53, v56, s33
	v_and_or_b32 v52, v53, s87, v52
	v_bfe_u32 v53, v54, 16, 1
	v_add3_u32 v53, v54, v53, s33
	v_bfe_u32 v54, v55, 16, 1
	v_lshrrev_b32_e32 v53, 16, v53
	v_add3_u32 v54, v55, v54, s33
	v_pk_mul_f32 v[48:49], v[48:49], v[64:65] op_sel_hi:[1,0]
	v_and_or_b32 v53, v54, s87, v53
	v_pk_mul_f32 v[48:49], v[12:13], v[48:49]
	global_store_dwordx2 v[78:79], v[52:53], off offset:3072
	v_bfe_u32 v52, v48, 16, 1
	v_pk_mul_f32 v[50:51], v[50:51], v[64:65] op_sel_hi:[1,0]
	v_add3_u32 v48, v48, v52, s33
	v_bfe_u32 v52, v49, 16, 1
	v_pk_mul_f32 v[50:51], v[14:15], v[50:51]
	v_lshrrev_b32_e32 v48, 16, v48
	v_add3_u32 v49, v49, v52, s33
	v_and_or_b32 v48, v49, s87, v48
	v_bfe_u32 v49, v50, 16, 1
	v_add3_u32 v49, v50, v49, s33
	v_bfe_u32 v50, v51, 16, 1
	v_lshrrev_b32_e32 v49, 16, v49
	v_add3_u32 v50, v51, v50, s33
	v_and_or_b32 v49, v50, s87, v49
	global_store_dwordx2 v[78:79], v[48:49], off offset:3584
	v_add_f32_dpp v48, v94, v94 quad_perm:[1,0,3,2] row_mask:0xf bank_mask:0xf bound_ctrl:1
	s_nop 1
	v_add_f32_dpp v48, v48, v48 quad_perm:[2,3,0,1] row_mask:0xf bank_mask:0xf bound_ctrl:1
	s_nop 1
	v_add_f32_dpp v48, v48, v48 row_half_mirror row_mask:0xf bank_mask:0xf bound_ctrl:1
	s_nop 1
	v_add_f32_dpp v48, v48, v48 row_mirror row_mask:0xf bank_mask:0xf bound_ctrl:1
	s_nop 0
	v_readlane_b32 s2, v48, 16
	v_readlane_b32 s3, v48, 48
	v_readlane_b32 s0, v48, 0
	v_readlane_b32 s1, v48, 32
	v_mov_b32_e32 v48, s2
	v_mov_b32_e32 v49, s3
	v_pk_add_f32 v[48:49], s[0:1], v[48:49]
	s_nop 0
	v_add_f32_e32 v48, v48, v49
	v_fmamk_f32 v48, v48, 0x3a800000, v220
	v_rsq_f32_e32 v48, v48
	s_nop 0
	v_pk_mul_f32 v[44:45], v[44:45], v[48:49] op_sel_hi:[1,0]
	s_nop 0
	v_pk_mul_f32 v[44:45], v[8:9], v[44:45]
	v_pk_mul_f32 v[46:47], v[46:47], v[48:49] op_sel_hi:[1,0]
	v_bfe_u32 v49, v44, 16, 1
	v_add3_u32 v44, v44, v49, s33
	v_bfe_u32 v49, v45, 16, 1
	v_pk_mul_f32 v[46:47], v[10:11], v[46:47]
	v_lshrrev_b32_e32 v44, 16, v44
	v_add3_u32 v45, v45, v49, s33
	v_and_or_b32 v44, v45, s87, v44
	v_bfe_u32 v45, v46, 16, 1
	v_add3_u32 v45, v46, v45, s33
	v_bfe_u32 v46, v47, 16, 1
	v_lshrrev_b32_e32 v45, 16, v45
	v_add3_u32 v46, v47, v46, s33
	v_pk_mul_f32 v[40:41], v[40:41], v[48:49] op_sel_hi:[1,0]
	v_and_or_b32 v45, v46, s87, v45
	v_pk_mul_f32 v[40:41], v[0:1], v[40:41]
	global_store_dwordx2 v[76:77], v[44:45], off
	v_bfe_u32 v44, v40, 16, 1
	v_pk_mul_f32 v[42:43], v[42:43], v[48:49] op_sel_hi:[1,0]
	v_add3_u32 v40, v40, v44, s33
	v_bfe_u32 v44, v41, 16, 1
	v_pk_mul_f32 v[42:43], v[2:3], v[42:43]
	v_lshrrev_b32_e32 v40, 16, v40
	v_add3_u32 v41, v41, v44, s33
	v_and_or_b32 v40, v41, s87, v40
	v_bfe_u32 v41, v42, 16, 1
	v_add3_u32 v41, v42, v41, s33
	v_bfe_u32 v42, v43, 16, 1
	v_lshrrev_b32_e32 v41, 16, v41
; __device__ __forceinline__ unsigned pk2(float lo, float hi) { return f2bf(lo) | (f2bf(hi) << 16); }
; __device__ __forceinline__ float frsq(float x) { return __builtin_amdgcn_rsqf(x); }
; __device__ __forceinline__ void rmsnorm_rows(const float* X, const float* g, bf16* H, float* Of, int gw, int ngw, int lane) {
;     ...
;         for (int r = 0; r < 4; ++r) {
;             const float rstd = frsq(wave_sum(s[r]) * (1.f / D) + 1e-6f);
; #pragma unroll
;             for (int j = 0; j < 4; ++j) {
;                 const f32x4 o = v[r][j] * rstd * gv[j];
;                 if (Of) *(f32x4*)(Of + (size_t)(row0 + r) * D + 4 * lane + 256 * j) = o;
;                 else { u32x2 w; w.x = pk2(o.x, o.y); w.y = pk2(o.z, o.w); *(u32x2*)(H + (size_t)(row0 + r) * D + 4 * lane + 256 * j) = w; }
;             }
;         }
;     }
	v_add3_u32 v42, v43, v42, s33
	v_pk_mul_f32 v[36:37], v[36:37], v[48:49] op_sel_hi:[1,0]
	v_and_or_b32 v41, v42, s87, v41
	v_pk_mul_f32 v[36:37], v[4:5], v[36:37]
	global_store_dwordx2 v[76:77], v[40:41], off offset:512
	v_bfe_u32 v40, v36, 16, 1
	v_pk_mul_f32 v[38:39], v[38:39], v[48:49] op_sel_hi:[1,0]
	v_add3_u32 v36, v36, v40, s33
	v_bfe_u32 v40, v37, 16, 1
	v_pk_mul_f32 v[38:39], v[6:7], v[38:39]
	v_lshrrev_b32_e32 v36, 16, v36
	v_add3_u32 v37, v37, v40, s33
	v_and_or_b32 v36, v37, s87, v36
	v_bfe_u32 v37, v38, 16, 1
	v_add3_u32 v37, v38, v37, s33
	v_bfe_u32 v38, v39, 16, 1
	v_lshrrev_b32_e32 v37, 16, v37
	v_add3_u32 v38, v39, v38, s33
	v_pk_mul_f32 v[32:33], v[32:33], v[48:49] op_sel_hi:[1,0]
	v_and_or_b32 v37, v38, s87, v37
	v_pk_mul_f32 v[32:33], v[12:13], v[32:33]
	global_store_dwordx2 v[76:77], v[36:37], off offset:1024
	v_bfe_u32 v36, v32, 16, 1
	v_pk_mul_f32 v[34:35], v[34:35], v[48:49] op_sel_hi:[1,0]
	v_add3_u32 v32, v32, v36, s33
	v_bfe_u32 v36, v33, 16, 1
	v_pk_mul_f32 v[34:35], v[14:15], v[34:35]
	v_lshrrev_b32_e32 v32, 16, v32
	v_add3_u32 v33, v33, v36, s33
	v_and_or_b32 v32, v33, s87, v32
	v_bfe_u32 v33, v34, 16, 1
	v_add3_u32 v33, v34, v33, s33
	v_bfe_u32 v34, v35, 16, 1
	v_lshrrev_b32_e32 v33, 16, v33
	v_add3_u32 v34, v35, v34, s33
	v_and_or_b32 v33, v34, s87, v33
	global_store_dwordx2 v[76:77], v[32:33], off offset:1536
	v_add_f32_dpp v32, v90, v90 quad_perm:[1,0,3,2] row_mask:0xf bank_mask:0xf bound_ctrl:1
	s_nop 1
	v_add_f32_dpp v32, v32, v32 quad_perm:[2,3,0,1] row_mask:0xf bank_mask:0xf bound_ctrl:1
	s_nop 1
	v_add_f32_dpp v32, v32, v32 row_half_mirror row_mask:0xf bank_mask:0xf bound_ctrl:1
	s_nop 1
	v_add_f32_dpp v32, v32, v32 row_mirror row_mask:0xf bank_mask:0xf bound_ctrl:1
	s_nop 0
	v_readlane_b32 s2, v32, 16
	v_readlane_b32 s3, v32, 48
	v_readlane_b32 s0, v32, 0
	v_readlane_b32 s1, v32, 32
	v_mov_b32_e32 v32, s2
	v_mov_b32_e32 v33, s3
	v_pk_add_f32 v[32:33], s[0:1], v[32:33]
	s_nop 0
	v_add_f32_e32 v32, v32, v33
	v_fmamk_f32 v32, v32, 0x3a800000, v220
	v_rsq_f32_e32 v32, v32
	s_nop 0
	v_pk_mul_f32 v[28:29], v[28:29], v[32:33] op_sel_hi:[1,0]
	s_nop 0
	v_pk_mul_f32 v[28:29], v[8:9], v[28:29]
	v_pk_mul_f32 v[30:31], v[30:31], v[32:33] op_sel_hi:[1,0]
	v_bfe_u32 v33, v28, 16, 1
	v_add3_u32 v28, v28, v33, s33
	v_bfe_u32 v33, v29, 16, 1
	v_pk_mul_f32 v[30:31], v[10:11], v[30:31]
	v_lshrrev_b32_e32 v28, 16, v28
	v_add3_u32 v29, v29, v33, s33
	v_and_or_b32 v28, v29, s87, v28
	v_bfe_u32 v29, v30, 16, 1
	v_add3_u32 v29, v30, v29, s33
	v_bfe_u32 v30, v31, 16, 1
	v_lshrrev_b32_e32 v29, 16, v29
	v_add3_u32 v30, v31, v30, s33
	v_pk_mul_f32 v[24:25], v[24:25], v[32:33] op_sel_hi:[1,0]
	v_and_or_b32 v29, v30, s87, v29
	v_pk_mul_f32 v[24:25], v[0:1], v[24:25]
	global_store_dwordx2 v[76:77], v[28:29], off offset:2048
	v_bfe_u32 v28, v24, 16, 1
	v_pk_mul_f32 v[26:27], v[26:27], v[32:33] op_sel_hi:[1,0]
	v_add3_u32 v24, v24, v28, s33
	v_bfe_u32 v28, v25, 16, 1
	v_pk_mul_f32 v[26:27], v[2:3], v[26:27]
	v_lshrrev_b32_e32 v24, 16, v24
	v_add3_u32 v25, v25, v28, s33
	v_and_or_b32 v24, v25, s87, v24
	v_bfe_u32 v25, v26, 16, 1
	v_add3_u32 v25, v26, v25, s33
	v_bfe_u32 v26, v27, 16, 1
	v_lshrrev_b32_e32 v25, 16, v25
	v_add3_u32 v26, v27, v26, s33
	v_pk_mul_f32 v[20:21], v[20:21], v[32:33] op_sel_hi:[1,0]
	v_and_or_b32 v25, v26, s87, v25
	v_pk_mul_f32 v[20:21], v[4:5], v[20:21]
	global_store_dwordx2 v[76:77], v[24:25], off offset:2560
	v_bfe_u32 v24, v20, 16, 1
	v_pk_mul_f32 v[22:23], v[22:23], v[32:33] op_sel_hi:[1,0]
	v_add3_u32 v20, v20, v24, s33
	v_bfe_u32 v24, v21, 16, 1
	v_pk_mul_f32 v[22:23], v[6:7], v[22:23]
	v_lshrrev_b32_e32 v20, 16, v20
	v_add3_u32 v21, v21, v24, s33
	v_and_or_b32 v20, v21, s87, v20
	v_bfe_u32 v21, v22, 16, 1
	v_add3_u32 v21, v22, v21, s33
	v_bfe_u32 v22, v23, 16, 1
	v_lshrrev_b32_e32 v21, 16, v21
	v_add3_u32 v22, v23, v22, s33
	v_pk_mul_f32 v[16:17], v[16:17], v[32:33] op_sel_hi:[1,0]
	v_and_or_b32 v21, v22, s87, v21
	v_pk_mul_f32 v[16:17], v[12:13], v[16:17]
	global_store_dwordx2 v[76:77], v[20:21], off offset:3072
	v_bfe_u32 v20, v16, 16, 1
	v_pk_mul_f32 v[18:19], v[18:19], v[32:33] op_sel_hi:[1,0]
	v_add3_u32 v16, v16, v20, s33
	v_bfe_u32 v20, v17, 16, 1
	v_pk_mul_f32 v[18:19], v[14:15], v[18:19]
	v_lshrrev_b32_e32 v16, 16, v16
	v_add3_u32 v17, v17, v20, s33
	v_and_or_b32 v16, v17, s87, v16
	v_bfe_u32 v17, v18, 16, 1
	v_add3_u32 v17, v18, v17, s33
	v_bfe_u32 v18, v19, 16, 1
	v_lshrrev_b32_e32 v17, 16, v17
	v_add3_u32 v18, v19, v18, s33
	v_and_or_b32 v17, v18, s87, v17
	global_store_dwordx2 v[76:77], v[16:17], off offset:3584
	s_cbranch_scc0 .LBB0_792
.LBB0_793:
	s_mov_b64 s[0:1], 0

; __device__ __forceinline__ void rmsnorm_rows(const float* X, const float* g, bf16* H, float* Of, int gw, int ngw, int lane) {
;     ...
;     for (int row0 = 4 * gw; row0 < T; row0 += 4 * ngw) {
;         f32x4 v[4][4]; float s[4] = {0.f, 0.f, 0.f, 0.f};
; #pragma unroll
;         for (int r = 0; r < 4; ++r)
; #pragma unroll
;             for (int j = 0; j < 4; ++j) v[r][j] = *(const f32x4*)(X + (size_t)(row0 + r) * D + 4 * lane + 256 * j);
;         __builtin_amdgcn_sched_barrier(0);
; #pragma unroll
;         for (int r = 0; r < 4; ++r)
; #pragma unroll
;             for (int j = 0; j < 4; ++j) s[r] += (v[r][j].x * v[r][j].x + v[r][j].y * v[r][j].y) + (v[r][j].z * v[r][j].z + v[r][j].w * v[r][j].w);
.LBB0_859:
	v_add_co_u32_e32 v16, vcc, 0xffffd000, v82
	s_nop 1
	v_addc_co_u32_e32 v17, vcc, -1, v83, vcc
	global_load_dwordx4 v[76:79], v[16:17], off offset:-3072
	global_load_dwordx4 v[72:75], v[16:17], off offset:-2048
	global_load_dwordx4 v[68:71], v[16:17], off offset:-1024
	global_load_dwordx4 v[64:67], v[16:17], off
	v_add_co_u32_e32 v16, vcc, 0xffffe000, v82
	s_nop 1
	v_addc_co_u32_e32 v17, vcc, -1, v83, vcc
	global_load_dwordx4 v[60:63], v[16:17], off offset:-3072
	global_load_dwordx4 v[56:59], v[16:17], off offset:-2048
	global_load_dwordx4 v[52:55], v[16:17], off offset:-1024
	global_load_dwordx4 v[48:51], v[16:17], off
	v_add_co_u32_e32 v16, vcc, 0xfffff000, v82
	s_nop 1
	v_addc_co_u32_e32 v17, vcc, -1, v83, vcc
	global_load_dwordx4 v[44:47], v[16:17], off offset:-3072
	global_load_dwordx4 v[40:43], v[16:17], off offset:-2048
	global_load_dwordx4 v[36:39], v[16:17], off offset:-1024
	global_load_dwordx4 v[32:35], v[82:83], off offset:-4096
	global_load_dwordx4 v[28:31], v[82:83], off offset:-3072
	global_load_dwordx4 v[24:27], v[82:83], off offset:-2048
	global_load_dwordx4 v[20:23], v[82:83], off offset:-1024
	s_nop 0
	global_load_dwordx4 v[16:19], v[82:83], off
	s_waitcnt vmcnt(15)
	v_pk_mul_f32 v[84:85], v[78:79], v[78:79]
	v_pk_mul_f32 v[86:87], v[76:77], v[76:77]
	s_add_i32 s4, s4, s64
	v_pk_mov_b32 v[88:89], v[86:87], v[84:85] op_sel:[1,0]
	v_mov_b32_e32 v87, v85
	v_pk_add_f32 v[84:85], v[88:89], v[86:87]
	s_waitcnt vmcnt(14)
	v_pk_mul_f32 v[86:87], v[74:75], v[74:75]
	v_pk_mul_f32 v[88:89], v[72:73], v[72:73]
	v_pk_add_f32 v[84:85], v[84:85], v[84:85] op_sel:[0,1] op_sel_hi:[1,0]
	v_pk_mov_b32 v[90:91], v[88:89], v[86:87] op_sel:[1,0]
	v_mov_b32_e32 v89, v87
	v_pk_add_f32 v[86:87], v[90:91], v[88:89]
	s_waitcnt vmcnt(12)
	v_mul_f32_e32 v88, v64, v64
	v_mul_f32_e32 v89, v65, v65
	v_pk_add_f32 v[86:87], v[86:87], v[86:87] op_sel:[0,1] op_sel_hi:[1,0]
	v_mov_b32_e32 v85, v88
	v_mov_b32_e32 v87, v89
	v_pk_add_f32 v[84:85], v[84:85], v[86:87]
	v_mul_f32_e32 v86, v69, v69
	v_mul_f32_e32 v88, v71, v71
	v_mul_f32_e32 v90, v66, v66
	v_mul_f32_e32 v91, v67, v67
	v_pk_fma_f32 v[86:87], v[68:69], v[68:69], v[86:87] op_sel_hi:[1,1,0]
	v_pk_fma_f32 v[88:89], v[70:71], v[70:71], v[88:89] op_sel_hi:[1,1,0]
	v_mov_b32_e32 v87, v90
	v_mov_b32_e32 v89, v91
	v_pk_add_f32 v[86:87], v[86:87], v[88:89]
	v_lshl_add_u64 v[82:83], v[82:83], 0, s[84:85]
	v_pk_add_f32 v[84:85], v[84:85], v[86:87]
	s_waitcnt vmcnt(11)
	v_pk_mul_f32 v[86:87], v[60:61], v[60:61]
	v_add_f32_e32 v92, v84, v85
	v_pk_mul_f32 v[84:85], v[62:63], v[62:63]
	s_cmpk_gt_i32 s4, 0x3fff
	v_pk_mov_b32 v[88:89], v[86:87], v[84:85] op_sel:[1,0]
	v_mov_b32_e32 v87, v85
	v_pk_add_f32 v[84:85], v[88:89], v[86:87]
	s_waitcnt vmcnt(10)
	v_pk_mul_f32 v[86:87], v[58:59], v[58:59]
	v_pk_mul_f32 v[88:89], v[56:57], v[56:57]
	v_pk_add_f32 v[84:85], v[84:85], v[84:85] op_sel:[0,1] op_sel_hi:[1,0]
	v_pk_mov_b32 v[90:91], v[88:89], v[86:87] op_sel:[1,0]
	v_mov_b32_e32 v89, v87
	v_pk_add_f32 v[86:87], v[90:91], v[88:89]
	s_waitcnt vmcnt(8)
	v_mul_f32_e32 v88, v48, v48
	v_mul_f32_e32 v89, v49, v49
	v_pk_add_f32 v[86:87], v[86:87], v[86:87] op_sel:[0,1] op_sel_hi:[1,0]
	v_mov_b32_e32 v85, v88
	v_mov_b32_e32 v87, v89
	v_pk_add_f32 v[84:85], v[84:85], v[86:87]
	v_mul_f32_e32 v86, v53, v53
	v_mul_f32_e32 v88, v55, v55
	v_mul_f32_e32 v90, v50, v50
	v_mul_f32_e32 v91, v51, v51
	v_pk_fma_f32 v[86:87], v[52:53], v[52:53], v[86:87] op_sel_hi:[1,1,0]
	v_pk_fma_f32 v[88:89], v[54:55], v[54:55], v[88:89] op_sel_hi:[1,1,0]
	v_mov_b32_e32 v87, v90
	v_mov_b32_e32 v89, v91
	v_pk_add_f32 v[86:87], v[86:87], v[88:89]
	s_nop 0
	v_pk_add_f32 v[84:85], v[84:85], v[86:87]
	s_waitcnt vmcnt(7)
	v_pk_mul_f32 v[86:87], v[44:45], v[44:45]
	v_add_f32_e32 v93, v84, v85
	v_pk_mul_f32 v[84:85], v[46:47], v[46:47]
	s_nop 0
	v_pk_mov_b32 v[88:89], v[86:87], v[84:85] op_sel:[1,0]
	v_mov_b32_e32 v87, v85
	v_pk_add_f32 v[84:85], v[88:89], v[86:87]
	s_waitcnt vmcnt(6)
	v_pk_mul_f32 v[86:87], v[42:43], v[42:43]
	v_pk_mul_f32 v[88:89], v[40:41], v[40:41]
	v_pk_add_f32 v[84:85], v[84:85], v[84:85] op_sel:[0,1] op_sel_hi:[1,0]
	v_pk_mov_b32 v[90:91], v[88:89], v[86:87] op_sel:[1,0]
	v_mov_b32_e32 v89, v87
	v_pk_add_f32 v[86:87], v[90:91], v[88:89]
	s_waitcnt vmcnt(4)
	v_mul_f32_e32 v88, v32, v32
	v_mul_f32_e32 v89, v33, v33
	v_pk_add_f32 v[86:87], v[86:87], v[86:87] op_sel:[0,1] op_sel_hi:[1,0]
	v_mov_b32_e32 v85, v88
	v_mov_b32_e32 v87, v89
	v_pk_add_f32 v[84:85], v[84:85], v[86:87]
	v_mul_f32_e32 v86, v37, v37
	v_mul_f32_e32 v88, v39, v39
	v_mul_f32_e32 v90, v34, v34
	v_mul_f32_e32 v91, v35, v35
	v_pk_fma_f32 v[86:87], v[36:37], v[36:37], v[86:87] op_sel_hi:[1,1,0]
	v_pk_fma_f32 v[88:89], v[38:39], v[38:39], v[88:89] op_sel_hi:[1,1,0]
	v_mov_b32_e32 v87, v90
	v_mov_b32_e32 v89, v91
	v_pk_add_f32 v[86:87], v[86:87], v[88:89]
	s_nop 0
	v_pk_add_f32 v[84:85], v[84:85], v[86:87]
	s_waitcnt vmcnt(3)
	v_pk_mul_f32 v[86:87], v[28:29], v[28:29]
	v_add_f32_e32 v94, v84, v85
	v_pk_mul_f32 v[84:85], v[30:31], v[30:31]
	s_nop 0
	v_pk_mov_b32 v[88:89], v[86:87], v[84:85] op_sel:[1,0]
	v_mov_b32_e32 v87, v85
	v_pk_add_f32 v[84:85], v[88:89], v[86:87]
	s_waitcnt vmcnt(2)
	v_pk_mul_f32 v[86:87], v[26:27], v[26:27]
	v_pk_mul_f32 v[88:89], v[24:25], v[24:25]
	v_pk_add_f32 v[84:85], v[84:85], v[84:85] op_sel:[0,1] op_sel_hi:[1,0]
	v_pk_mov_b32 v[90:91], v[88:89], v[86:87] op_sel:[1,0]
	v_mov_b32_e32 v89, v87
	v_pk_add_f32 v[86:87], v[90:91], v[88:89]
	s_waitcnt vmcnt(0)
; __device__ __forceinline__ unsigned pk2(float lo, float hi) { return f2bf(lo) | (f2bf(hi) << 16); }
; __device__ __forceinline__ float frsq(float x) { return __builtin_amdgcn_rsqf(x); }
; __device__ __forceinline__ void rmsnorm_rows(const float* X, const float* g, bf16* H, float* Of, int gw, int ngw, int lane) {
;     ...
;             for (int j = 0; j < 4; ++j) s[r] += (v[r][j].x * v[r][j].x + v[r][j].y * v[r][j].y) + (v[r][j].z * v[r][j].z + v[r][j].w * v[r][j].w);
; #pragma unroll
;         for (int r = 0; r < 4; ++r) {
;             const float rstd = frsq(wave_sum(s[r]) * (1.f / D) + 1e-6f);
; #pragma unroll
;             for (int j = 0; j < 4; ++j) {
;                 const f32x4 o = v[r][j] * rstd * gv[j];
;                 if (Of) *(f32x4*)(Of + (size_t)(row0 + r) * D + 4 * lane + 256 * j) = o;
;                 else { u32x2 w; w.x = pk2(o.x, o.y); w.y = pk2(o.z, o.w); *(u32x2*)(H + (size_t)(row0 + r) * D + 4 * lane + 256 * j) = w; }
	v_mul_f32_e32 v88, v16, v16
	v_mul_f32_e32 v89, v17, v17
	v_pk_add_f32 v[86:87], v[86:87], v[86:87] op_sel:[0,1] op_sel_hi:[1,0]
	v_mov_b32_e32 v85, v88
	v_mov_b32_e32 v87, v89
	v_pk_add_f32 v[84:85], v[84:85], v[86:87]
	v_mul_f32_e32 v86, v21, v21
	v_mul_f32_e32 v88, v23, v23
	v_mul_f32_e32 v90, v18, v18
	v_mul_f32_e32 v91, v19, v19
	v_pk_fma_f32 v[86:87], v[20:21], v[20:21], v[86:87] op_sel_hi:[1,1,0]
	v_pk_fma_f32 v[88:89], v[22:23], v[22:23], v[88:89] op_sel_hi:[1,1,0]
	v_mov_b32_e32 v87, v90
	v_mov_b32_e32 v89, v91
	v_pk_add_f32 v[86:87], v[86:87], v[88:89]
	s_nop 0
	v_pk_add_f32 v[84:85], v[84:85], v[86:87]
	s_nop 0
	v_add_f32_e32 v86, v84, v85
	v_add_f32_dpp v84, v92, v92 quad_perm:[1,0,3,2] row_mask:0xf bank_mask:0xf bound_ctrl:1
	s_nop 1
	v_add_f32_dpp v84, v84, v84 quad_perm:[2,3,0,1] row_mask:0xf bank_mask:0xf bound_ctrl:1
	s_nop 1
	v_add_f32_dpp v84, v84, v84 row_half_mirror row_mask:0xf bank_mask:0xf bound_ctrl:1
	s_nop 1
	v_add_f32_dpp v84, v84, v84 row_mirror row_mask:0xf bank_mask:0xf bound_ctrl:1
	s_nop 0
	v_readlane_b32 s2, v84, 16
	v_readlane_b32 s3, v84, 48
	v_readlane_b32 s0, v84, 0
	v_readlane_b32 s1, v84, 32
	v_mov_b32_e32 v84, s2
	v_mov_b32_e32 v85, s3
	v_pk_add_f32 v[84:85], s[0:1], v[84:85]
	s_movk_i32 s0, 0xf000
	v_add_f32_e32 v84, v84, v85
	v_fmamk_f32 v84, v84, 0x3a800000, v220
	v_rsq_f32_e32 v84, v84
	s_nop 0
	v_pk_mul_f32 v[76:77], v[76:77], v[84:85] op_sel_hi:[1,0]
	s_nop 0
	v_pk_mul_f32 v[76:77], v[0:1], v[76:77]
	v_pk_mul_f32 v[78:79], v[78:79], v[84:85] op_sel_hi:[1,0]
	v_bfe_u32 v85, v76, 16, 1
	v_add3_u32 v76, v76, v85, s33
	v_bfe_u32 v85, v77, 16, 1
	v_pk_mul_f32 v[78:79], v[2:3], v[78:79]
	v_lshrrev_b32_e32 v76, 16, v76
	v_add3_u32 v77, v77, v85, s33
	v_and_or_b32 v76, v77, s87, v76
	v_bfe_u32 v77, v78, 16, 1
	v_add3_u32 v77, v78, v77, s33
	v_bfe_u32 v78, v79, 16, 1
	v_lshrrev_b32_e32 v77, 16, v77
	v_add3_u32 v78, v79, v78, s33
	v_and_or_b32 v77, v78, s87, v77
	v_add_co_u32_e32 v78, vcc, s0, v80
	v_pk_mul_f32 v[72:73], v[72:73], v[84:85] op_sel_hi:[1,0]
	s_nop 0
	v_addc_co_u32_e32 v79, vcc, -1, v81, vcc
	v_pk_mul_f32 v[72:73], v[4:5], v[72:73]
	global_store_dwordx2 v[78:79], v[76:77], off offset:-3584
	v_bfe_u32 v76, v72, 16, 1
	v_pk_mul_f32 v[74:75], v[74:75], v[84:85] op_sel_hi:[1,0]
	v_add3_u32 v72, v72, v76, s33
	v_bfe_u32 v76, v73, 16, 1
	v_pk_mul_f32 v[74:75], v[6:7], v[74:75]
	v_lshrrev_b32_e32 v72, 16, v72
	v_add3_u32 v73, v73, v76, s33
	v_and_or_b32 v72, v73, s87, v72
	v_bfe_u32 v73, v74, 16, 1
	v_add3_u32 v73, v74, v73, s33
	v_bfe_u32 v74, v75, 16, 1
	v_lshrrev_b32_e32 v73, 16, v73
	v_add3_u32 v74, v75, v74, s33
	v_pk_mul_f32 v[68:69], v[68:69], v[84:85] op_sel_hi:[1,0]
	v_and_or_b32 v73, v74, s87, v73
	v_pk_mul_f32 v[68:69], v[8:9], v[68:69]
	global_store_dwordx2 v[78:79], v[72:73], off offset:-3072
	v_bfe_u32 v72, v68, 16, 1
	v_pk_mul_f32 v[70:71], v[70:71], v[84:85] op_sel_hi:[1,0]
	v_add3_u32 v68, v68, v72, s33
	v_bfe_u32 v72, v69, 16, 1
	v_pk_mul_f32 v[70:71], v[10:11], v[70:71]
	v_lshrrev_b32_e32 v68, 16, v68
	v_add3_u32 v69, v69, v72, s33
	v_and_or_b32 v68, v69, s87, v68
	v_bfe_u32 v69, v70, 16, 1
	v_add3_u32 v69, v70, v69, s33
	v_bfe_u32 v70, v71, 16, 1
	v_lshrrev_b32_e32 v69, 16, v69
	v_add3_u32 v70, v71, v70, s33
	v_pk_mul_f32 v[64:65], v[64:65], v[84:85] op_sel_hi:[1,0]
	v_and_or_b32 v69, v70, s87, v69
	v_pk_mul_f32 v[64:65], v[12:13], v[64:65]
	global_store_dwordx2 v[78:79], v[68:69], off offset:-2560
	v_bfe_u32 v68, v64, 16, 1
	v_pk_mul_f32 v[66:67], v[66:67], v[84:85] op_sel_hi:[1,0]
	v_add3_u32 v64, v64, v68, s33
	v_bfe_u32 v68, v65, 16, 1
	v_pk_mul_f32 v[66:67], v[14:15], v[66:67]
	v_lshrrev_b32_e32 v64, 16, v64
	v_add3_u32 v65, v65, v68, s33
	v_and_or_b32 v64, v65, s87, v64
	v_bfe_u32 v65, v66, 16, 1
	v_add3_u32 v65, v66, v65, s33
	v_bfe_u32 v66, v67, 16, 1
	v_lshrrev_b32_e32 v65, 16, v65
	v_add3_u32 v66, v67, v66, s33
	v_and_or_b32 v65, v66, s87, v65
	global_store_dwordx2 v[78:79], v[64:65], off offset:-2048
	v_add_f32_dpp v64, v93, v93 quad_perm:[1,0,3,2] row_mask:0xf bank_mask:0xf bound_ctrl:1
	s_nop 1
	v_add_f32_dpp v64, v64, v64 quad_perm:[2,3,0,1] row_mask:0xf bank_mask:0xf bound_ctrl:1
	s_nop 1
	v_add_f32_dpp v64, v64, v64 row_half_mirror row_mask:0xf bank_mask:0xf bound_ctrl:1
	s_nop 1
	v_add_f32_dpp v64, v64, v64 row_mirror row_mask:0xf bank_mask:0xf bound_ctrl:1
	s_nop 0
	v_readlane_b32 s2, v64, 16
	v_readlane_b32 s3, v64, 48
	v_readlane_b32 s0, v64, 0
	v_readlane_b32 s1, v64, 32
	v_mov_b32_e32 v64, s2
	v_mov_b32_e32 v65, s3
	v_pk_add_f32 v[64:65], s[0:1], v[64:65]
	s_nop 0
	v_add_f32_e32 v64, v64, v65
	v_fmamk_f32 v64, v64, 0x3a800000, v220
	v_rsq_f32_e32 v64, v64
	s_nop 0
	v_pk_mul_f32 v[60:61], v[60:61], v[64:65] op_sel_hi:[1,0]
	s_nop 0
	v_pk_mul_f32 v[60:61], v[0:1], v[60:61]
	v_pk_mul_f32 v[62:63], v[62:63], v[64:65] op_sel_hi:[1,0]
	v_bfe_u32 v65, v60, 16, 1
	v_add3_u32 v60, v60, v65, s33
	v_bfe_u32 v65, v61, 16, 1
	v_pk_mul_f32 v[62:63], v[2:3], v[62:63]
	v_lshrrev_b32_e32 v60, 16, v60
	v_add3_u32 v61, v61, v65, s33
	v_and_or_b32 v60, v61, s87, v60
	v_bfe_u32 v61, v62, 16, 1
	v_add3_u32 v61, v62, v61, s33
	v_bfe_u32 v62, v63, 16, 1
	v_lshrrev_b32_e32 v61, 16, v61
	v_add3_u32 v62, v63, v62, s33
	v_pk_mul_f32 v[56:57], v[56:57], v[64:65] op_sel_hi:[1,0]
	v_and_or_b32 v61, v62, s87, v61
	v_pk_mul_f32 v[56:57], v[4:5], v[56:57]
	global_store_dwordx2 v[78:79], v[60:61], off offset:-1536
	v_bfe_u32 v60, v56, 16, 1
	v_pk_mul_f32 v[58:59], v[58:59], v[64:65] op_sel_hi:[1,0]
	v_add3_u32 v56, v56, v60, s33
	v_bfe_u32 v60, v57, 16, 1
	v_pk_mul_f32 v[58:59], v[6:7], v[58:59]
	v_lshrrev_b32_e32 v56, 16, v56
	v_add3_u32 v57, v57, v60, s33
	v_and_or_b32 v56, v57, s87, v56
; __device__ __forceinline__ unsigned pk2(float lo, float hi) { return f2bf(lo) | (f2bf(hi) << 16); }
; __device__ __forceinline__ float frsq(float x) { return __builtin_amdgcn_rsqf(x); }
; __device__ __forceinline__ void rmsnorm_rows(const float* X, const float* g, bf16* H, float* Of, int gw, int ngw, int lane) {
;     ...
;         for (int r = 0; r < 4; ++r) {
;             const float rstd = frsq(wave_sum(s[r]) * (1.f / D) + 1e-6f);
; #pragma unroll
;             for (int j = 0; j < 4; ++j) {
;                 const f32x4 o = v[r][j] * rstd * gv[j];
;                 if (Of) *(f32x4*)(Of + (size_t)(row0 + r) * D + 4 * lane + 256 * j) = o;
;                 else { u32x2 w; w.x = pk2(o.x, o.y); w.y = pk2(o.z, o.w); *(u32x2*)(H + (size_t)(row0 + r) * D + 4 * lane + 256 * j) = w; }
;             }
	v_bfe_u32 v57, v58, 16, 1
	v_add3_u32 v57, v58, v57, s33
	v_bfe_u32 v58, v59, 16, 1
	v_lshrrev_b32_e32 v57, 16, v57
	v_add3_u32 v58, v59, v58, s33
	v_pk_mul_f32 v[52:53], v[52:53], v[64:65] op_sel_hi:[1,0]
	v_and_or_b32 v57, v58, s87, v57
	v_pk_mul_f32 v[52:53], v[8:9], v[52:53]
	global_store_dwordx2 v[78:79], v[56:57], off offset:-1024
	v_bfe_u32 v56, v52, 16, 1
	v_pk_mul_f32 v[54:55], v[54:55], v[64:65] op_sel_hi:[1,0]
	v_add3_u32 v52, v52, v56, s33
	v_bfe_u32 v56, v53, 16, 1
	v_pk_mul_f32 v[54:55], v[10:11], v[54:55]
	v_lshrrev_b32_e32 v52, 16, v52
	v_add3_u32 v53, v53, v56, s33
	v_and_or_b32 v52, v53, s87, v52
	v_bfe_u32 v53, v54, 16, 1
	v_add3_u32 v53, v54, v53, s33
	v_bfe_u32 v54, v55, 16, 1
	v_lshrrev_b32_e32 v53, 16, v53
	v_add3_u32 v54, v55, v54, s33
	v_pk_mul_f32 v[48:49], v[48:49], v[64:65] op_sel_hi:[1,0]
	v_and_or_b32 v53, v54, s87, v53
	v_pk_mul_f32 v[48:49], v[12:13], v[48:49]
	global_store_dwordx2 v[78:79], v[52:53], off offset:-512
	v_bfe_u32 v52, v48, 16, 1
	v_pk_mul_f32 v[50:51], v[50:51], v[64:65] op_sel_hi:[1,0]
	v_add3_u32 v48, v48, v52, s33
	v_bfe_u32 v52, v49, 16, 1
	v_pk_mul_f32 v[50:51], v[14:15], v[50:51]
	v_lshrrev_b32_e32 v48, 16, v48
	v_add3_u32 v49, v49, v52, s33
	v_and_or_b32 v48, v49, s87, v48
	v_bfe_u32 v49, v50, 16, 1
	v_add3_u32 v49, v50, v49, s33
	v_bfe_u32 v50, v51, 16, 1
	v_lshrrev_b32_e32 v49, 16, v49
	v_add3_u32 v50, v51, v50, s33
	v_and_or_b32 v49, v50, s87, v49
	global_store_dwordx2 v[80:81], v[48:49], off offset:-4096
	v_add_f32_dpp v48, v94, v94 quad_perm:[1,0,3,2] row_mask:0xf bank_mask:0xf bound_ctrl:1
	s_nop 1
	v_add_f32_dpp v48, v48, v48 quad_perm:[2,3,0,1] row_mask:0xf bank_mask:0xf bound_ctrl:1
	s_nop 1
	v_add_f32_dpp v48, v48, v48 row_half_mirror row_mask:0xf bank_mask:0xf bound_ctrl:1
	s_nop 1
	v_add_f32_dpp v48, v48, v48 row_mirror row_mask:0xf bank_mask:0xf bound_ctrl:1
	s_nop 0
	v_readlane_b32 s2, v48, 16
	v_readlane_b32 s3, v48, 48
	v_readlane_b32 s0, v48, 0
	v_readlane_b32 s1, v48, 32
	v_mov_b32_e32 v48, s2
	v_mov_b32_e32 v49, s3
	v_pk_add_f32 v[48:49], s[0:1], v[48:49]
	s_nop 0
	v_add_f32_e32 v48, v48, v49
	v_fmamk_f32 v48, v48, 0x3a800000, v220
	v_rsq_f32_e32 v48, v48
	s_nop 0
	v_pk_mul_f32 v[44:45], v[44:45], v[48:49] op_sel_hi:[1,0]
	s_nop 0
	v_pk_mul_f32 v[44:45], v[0:1], v[44:45]
	v_pk_mul_f32 v[46:47], v[46:47], v[48:49] op_sel_hi:[1,0]
	v_bfe_u32 v49, v44, 16, 1
	v_add3_u32 v44, v44, v49, s33
	v_bfe_u32 v49, v45, 16, 1
	v_pk_mul_f32 v[46:47], v[2:3], v[46:47]
	v_lshrrev_b32_e32 v44, 16, v44
	v_add3_u32 v45, v45, v49, s33
	v_and_or_b32 v44, v45, s87, v44
	v_bfe_u32 v45, v46, 16, 1
	v_add3_u32 v45, v46, v45, s33
	v_bfe_u32 v46, v47, 16, 1
	v_lshrrev_b32_e32 v45, 16, v45
	v_add3_u32 v46, v47, v46, s33
	v_pk_mul_f32 v[40:41], v[40:41], v[48:49] op_sel_hi:[1,0]
	v_and_or_b32 v45, v46, s87, v45
	v_pk_mul_f32 v[40:41], v[4:5], v[40:41]
	global_store_dwordx2 v[80:81], v[44:45], off offset:-3584
	v_bfe_u32 v44, v40, 16, 1
	v_pk_mul_f32 v[42:43], v[42:43], v[48:49] op_sel_hi:[1,0]
	v_add3_u32 v40, v40, v44, s33
	v_bfe_u32 v44, v41, 16, 1
	v_pk_mul_f32 v[42:43], v[6:7], v[42:43]
	v_lshrrev_b32_e32 v40, 16, v40
	v_add3_u32 v41, v41, v44, s33
	v_and_or_b32 v40, v41, s87, v40
	v_bfe_u32 v41, v42, 16, 1
	v_add3_u32 v41, v42, v41, s33
	v_bfe_u32 v42, v43, 16, 1
	v_lshrrev_b32_e32 v41, 16, v41
	v_add3_u32 v42, v43, v42, s33
	v_pk_mul_f32 v[36:37], v[36:37], v[48:49] op_sel_hi:[1,0]
	v_and_or_b32 v41, v42, s87, v41
	v_pk_mul_f32 v[36:37], v[8:9], v[36:37]
	global_store_dwordx2 v[80:81], v[40:41], off offset:-3072
	v_bfe_u32 v40, v36, 16, 1
	v_pk_mul_f32 v[38:39], v[38:39], v[48:49] op_sel_hi:[1,0]
	v_add3_u32 v36, v36, v40, s33
	v_bfe_u32 v40, v37, 16, 1
	v_pk_mul_f32 v[38:39], v[10:11], v[38:39]
	v_lshrrev_b32_e32 v36, 16, v36
	v_add3_u32 v37, v37, v40, s33
	v_and_or_b32 v36, v37, s87, v36
	v_bfe_u32 v37, v38, 16, 1
	v_add3_u32 v37, v38, v37, s33
	v_bfe_u32 v38, v39, 16, 1
	v_lshrrev_b32_e32 v37, 16, v37
	v_add3_u32 v38, v39, v38, s33
; __device__ __forceinline__ unsigned pk2(float lo, float hi) { return f2bf(lo) | (f2bf(hi) << 16); }
; template <int CTRL> __device__ __forceinline__ float dpp_mov(float v) { return __int_as_float(__builtin_amdgcn_update_dpp(0, __float_as_int(v), CTRL, 0xF, 0xF, true)); }
; __device__ __forceinline__ float frsq(float x) { return __builtin_amdgcn_rsqf(x); }
; __device__ __forceinline__ float wave_sum(float v) {
;     v += dpp_mov<0xB1>(v); v += dpp_mov<0x4E>(v); v += dpp_mov<0x141>(v); v += dpp_mov<0x140>(v);
;     const float s0 = __int_as_float(__builtin_amdgcn_readlane(__float_as_int(v), 0)), s1 = __int_as_float(__builtin_amdgcn_readlane(__float_as_int(v), 16));
;     const float s2 = __int_as_float(__builtin_amdgcn_readlane(__float_as_int(v), 32)), s3 = __int_as_float(__builtin_amdgcn_readlane(__float_as_int(v), 48));
;     return (s0 + s1) + (s2 + s3);
; }
; __device__ __forceinline__ void rmsnorm_rows(const float* X, const float* g, bf16* H, float* Of, int gw, int ngw, int lane) {
;     ...
;         for (int r = 0; r < 4; ++r) {
;             const float rstd = frsq(wave_sum(s[r]) * (1.f / D) + 1e-6f);
; #pragma unroll
;             for (int j = 0; j < 4; ++j) {
;                 const f32x4 o = v[r][j] * rstd * gv[j];
;                 if (Of) *(f32x4*)(Of + (size_t)(row0 + r) * D + 4 * lane + 256 * j) = o;
;                 else { u32x2 w; w.x = pk2(o.x, o.y); w.y = pk2(o.z, o.w); *(u32x2*)(H + (size_t)(row0 + r) * D + 4 * lane + 256 * j) = w; }
;             }
	v_pk_mul_f32 v[32:33], v[32:33], v[48:49] op_sel_hi:[1,0]
	v_and_or_b32 v37, v38, s87, v37
	v_pk_mul_f32 v[32:33], v[12:13], v[32:33]
	global_store_dwordx2 v[80:81], v[36:37], off offset:-2560
	v_bfe_u32 v36, v32, 16, 1
	v_pk_mul_f32 v[34:35], v[34:35], v[48:49] op_sel_hi:[1,0]
	v_add3_u32 v32, v32, v36, s33
	v_bfe_u32 v36, v33, 16, 1
	v_pk_mul_f32 v[34:35], v[14:15], v[34:35]
	v_lshrrev_b32_e32 v32, 16, v32
	v_add3_u32 v33, v33, v36, s33
	v_and_or_b32 v32, v33, s87, v32
	v_bfe_u32 v33, v34, 16, 1
	v_add3_u32 v33, v34, v33, s33
	v_bfe_u32 v34, v35, 16, 1
	v_lshrrev_b32_e32 v33, 16, v33
	v_add3_u32 v34, v35, v34, s33
	v_and_or_b32 v33, v34, s87, v33
	global_store_dwordx2 v[80:81], v[32:33], off offset:-2048
	v_add_f32_dpp v32, v86, v86 quad_perm:[1,0,3,2] row_mask:0xf bank_mask:0xf bound_ctrl:1
	s_nop 1
	v_add_f32_dpp v32, v32, v32 quad_perm:[2,3,0,1] row_mask:0xf bank_mask:0xf bound_ctrl:1
	s_nop 1
	v_add_f32_dpp v32, v32, v32 row_half_mirror row_mask:0xf bank_mask:0xf bound_ctrl:1
	s_nop 1
	v_add_f32_dpp v32, v32, v32 row_mirror row_mask:0xf bank_mask:0xf bound_ctrl:1
	s_nop 0
	v_readlane_b32 s2, v32, 16
	v_readlane_b32 s3, v32, 48
	v_readlane_b32 s0, v32, 0
	v_readlane_b32 s1, v32, 32
	v_mov_b32_e32 v32, s2
	v_mov_b32_e32 v33, s3
	v_pk_add_f32 v[32:33], s[0:1], v[32:33]
	s_nop 0
	v_add_f32_e32 v32, v32, v33
	v_fmamk_f32 v32, v32, 0x3a800000, v220
	v_rsq_f32_e32 v32, v32
	s_nop 0
	v_pk_mul_f32 v[28:29], v[28:29], v[32:33] op_sel_hi:[1,0]
	s_nop 0
	v_pk_mul_f32 v[28:29], v[0:1], v[28:29]
	v_pk_mul_f32 v[30:31], v[30:31], v[32:33] op_sel_hi:[1,0]
	v_bfe_u32 v33, v28, 16, 1
	v_add3_u32 v28, v28, v33, s33
	v_bfe_u32 v33, v29, 16, 1
	v_pk_mul_f32 v[30:31], v[2:3], v[30:31]
	v_lshrrev_b32_e32 v28, 16, v28
	v_add3_u32 v29, v29, v33, s33
	v_and_or_b32 v28, v29, s87, v28
	v_bfe_u32 v29, v30, 16, 1
	v_add3_u32 v29, v30, v29, s33
	v_bfe_u32 v30, v31, 16, 1
	v_lshrrev_b32_e32 v29, 16, v29
	v_add3_u32 v30, v31, v30, s33
	v_pk_mul_f32 v[24:25], v[24:25], v[32:33] op_sel_hi:[1,0]
	v_and_or_b32 v29, v30, s87, v29
	v_pk_mul_f32 v[24:25], v[4:5], v[24:25]
	global_store_dwordx2 v[80:81], v[28:29], off offset:-1536
	v_bfe_u32 v28, v24, 16, 1
	v_pk_mul_f32 v[26:27], v[26:27], v[32:33] op_sel_hi:[1,0]
	v_add3_u32 v24, v24, v28, s33
	v_bfe_u32 v28, v25, 16, 1
	v_pk_mul_f32 v[26:27], v[6:7], v[26:27]
	v_lshrrev_b32_e32 v24, 16, v24
	v_add3_u32 v25, v25, v28, s33
	v_and_or_b32 v24, v25, s87, v24
	v_bfe_u32 v25, v26, 16, 1
	v_add3_u32 v25, v26, v25, s33
	v_bfe_u32 v26, v27, 16, 1
	v_lshrrev_b32_e32 v25, 16, v25
	v_add3_u32 v26, v27, v26, s33
	v_pk_mul_f32 v[20:21], v[20:21], v[32:33] op_sel_hi:[1,0]
	v_and_or_b32 v25, v26, s87, v25
	v_pk_mul_f32 v[20:21], v[8:9], v[20:21]
	global_store_dwordx2 v[80:81], v[24:25], off offset:-1024
	v_bfe_u32 v24, v20, 16, 1
	v_pk_mul_f32 v[22:23], v[22:23], v[32:33] op_sel_hi:[1,0]
	v_add3_u32 v20, v20, v24, s33
	v_bfe_u32 v24, v21, 16, 1
	v_pk_mul_f32 v[22:23], v[10:11], v[22:23]
	v_lshrrev_b32_e32 v20, 16, v20
	v_add3_u32 v21, v21, v24, s33
	v_and_or_b32 v20, v21, s87, v20
	v_bfe_u32 v21, v22, 16, 1
	v_add3_u32 v21, v22, v21, s33
	v_bfe_u32 v22, v23, 16, 1
	v_lshrrev_b32_e32 v21, 16, v21
	v_add3_u32 v22, v23, v22, s33
	v_pk_mul_f32 v[16:17], v[16:17], v[32:33] op_sel_hi:[1,0]
	v_and_or_b32 v21, v22, s87, v21
	v_pk_mul_f32 v[16:17], v[12:13], v[16:17]
	global_store_dwordx2 v[80:81], v[20:21], off offset:-512
	v_bfe_u32 v20, v16, 16, 1
	v_pk_mul_f32 v[18:19], v[18:19], v[32:33] op_sel_hi:[1,0]
	v_add3_u32 v16, v16, v20, s33
	v_bfe_u32 v20, v17, 16, 1
	v_pk_mul_f32 v[18:19], v[14:15], v[18:19]
	v_lshrrev_b32_e32 v16, 16, v16
	v_add3_u32 v17, v17, v20, s33
	v_and_or_b32 v16, v17, s87, v16
	v_bfe_u32 v17, v18, 16, 1
	v_add3_u32 v17, v18, v17, s33
	v_bfe_u32 v18, v19, 16, 1
	v_lshrrev_b32_e32 v17, 16, v17
	v_add3_u32 v18, v19, v18, s33
	v_and_or_b32 v17, v18, s87, v17
	global_store_dwordx2 v[80:81], v[16:17], off
	v_lshl_add_u64 v[80:81], v[80:81], 0, s[56:57]
	s_cbranch_scc0 .LBB0_859

; __device__ __forceinline__ float frsq(float x) { return __builtin_amdgcn_rsqf(x); }
; __device__ __forceinline__ void rmsnorm_rows(const float* X, const float* g, bf16* H, float* Of, int gw, int ngw, int lane) {
;     ...
;     for (int row0 = 4 * gw; row0 < T; row0 += 4 * ngw) {
;         f32x4 v[4][4]; float s[4] = {0.f, 0.f, 0.f, 0.f};
; #pragma unroll
;         for (int r = 0; r < 4; ++r)
; #pragma unroll
;             for (int j = 0; j < 4; ++j) v[r][j] = *(const f32x4*)(X + (size_t)(row0 + r) * D + 4 * lane + 256 * j);
;         __builtin_amdgcn_sched_barrier(0);
; #pragma unroll
;         for (int r = 0; r < 4; ++r)
; #pragma unroll
;             for (int j = 0; j < 4; ++j) s[r] += (v[r][j].x * v[r][j].x + v[r][j].y * v[r][j].y) + (v[r][j].z * v[r][j].z + v[r][j].w * v[r][j].w);
; #pragma unroll
;         for (int r = 0; r < 4; ++r) {
;             const float rstd = frsq(wave_sum(s[r]) * (1.f / D) + 1e-6f);
; #pragma unroll
;             for (int j = 0; j < 4; ++j) {
;                 const f32x4 o = v[r][j] * rstd * gv[j];
;                 if (Of) *(f32x4*)(Of + (size_t)(row0 + r) * D + 4 * lane + 256 * j) = o;
.LBB0_866:
	v_lshl_add_u64 v[16:17], s[6:7], 0, v[152:153]
	v_add_co_u32_e32 v18, vcc, 0x1080000, v16
	s_nop 1
	v_addc_co_u32_e32 v19, vcc, 0, v17, vcc
	global_load_dwordx4 v[76:79], v[18:19], off
	global_load_dwordx4 v[72:75], v[18:19], off offset:1024
	global_load_dwordx4 v[68:71], v[18:19], off offset:2048
	global_load_dwordx4 v[64:67], v[18:19], off offset:3072
	v_add_co_u32_e32 v18, vcc, 0x1081000, v16
	s_nop 1
	v_addc_co_u32_e32 v19, vcc, 0, v17, vcc
	global_load_dwordx4 v[60:63], v[18:19], off
	global_load_dwordx4 v[56:59], v[18:19], off offset:1024
	global_load_dwordx4 v[52:55], v[18:19], off offset:2048
	global_load_dwordx4 v[48:51], v[18:19], off offset:3072
	v_add_co_u32_e32 v18, vcc, 0x1082000, v16
	s_nop 1
	v_addc_co_u32_e32 v19, vcc, 0, v17, vcc
	v_add_co_u32_e32 v16, vcc, 0x1083000, v16
	global_load_dwordx4 v[44:47], v[18:19], off
	global_load_dwordx4 v[40:43], v[18:19], off offset:1024
	global_load_dwordx4 v[36:39], v[18:19], off offset:2048
	global_load_dwordx4 v[32:35], v[18:19], off offset:3072
	v_addc_co_u32_e32 v17, vcc, 0, v17, vcc
	global_load_dwordx4 v[28:31], v[16:17], off
	global_load_dwordx4 v[24:27], v[16:17], off offset:1024
	global_load_dwordx4 v[20:23], v[16:17], off offset:2048
	s_nop 0
	global_load_dwordx4 v[16:19], v[16:17], off offset:3072
	s_waitcnt vmcnt(15)
	v_pk_mul_f32 v[82:83], v[78:79], v[78:79]
	v_pk_mul_f32 v[84:85], v[76:77], v[76:77]
	s_andn2_b64 vcc, exec, s[2:3]
	v_pk_mov_b32 v[86:87], v[84:85], v[82:83] op_sel:[1,0]
	v_mov_b32_e32 v85, v83
	v_pk_add_f32 v[82:83], v[86:87], v[84:85]
	s_waitcnt vmcnt(14)
	v_pk_mul_f32 v[84:85], v[74:75], v[74:75]
	v_pk_mul_f32 v[86:87], v[72:73], v[72:73]
	v_pk_add_f32 v[82:83], v[82:83], v[82:83] op_sel:[0,1] op_sel_hi:[1,0]
	v_pk_mov_b32 v[88:89], v[86:87], v[84:85] op_sel:[1,0]
	v_mov_b32_e32 v87, v85
	v_pk_add_f32 v[84:85], v[88:89], v[86:87]
	s_waitcnt vmcnt(12)
	v_mul_f32_e32 v86, v64, v64
	v_mul_f32_e32 v87, v65, v65
	v_pk_add_f32 v[84:85], v[84:85], v[84:85] op_sel:[0,1] op_sel_hi:[1,0]
	v_mov_b32_e32 v83, v86
	v_mov_b32_e32 v85, v87
	v_pk_add_f32 v[82:83], v[82:83], v[84:85]
	v_mul_f32_e32 v84, v69, v69
	v_mul_f32_e32 v86, v71, v71
	v_mul_f32_e32 v88, v66, v66
	v_mul_f32_e32 v89, v67, v67
	v_pk_fma_f32 v[84:85], v[68:69], v[68:69], v[84:85] op_sel_hi:[1,1,0]
	v_pk_fma_f32 v[86:87], v[70:71], v[70:71], v[86:87] op_sel_hi:[1,1,0]
	v_mov_b32_e32 v85, v88
	v_mov_b32_e32 v87, v89
	v_pk_add_f32 v[84:85], v[84:85], v[86:87]
	s_nop 0
	v_pk_add_f32 v[82:83], v[82:83], v[84:85]
	s_nop 0
	v_add_f32_e32 v82, v82, v83
	s_nop 1
	v_add_f32_dpp v82, v82, v82 quad_perm:[1,0,3,2] row_mask:0xf bank_mask:0xf bound_ctrl:1
	s_nop 1
	v_add_f32_dpp v82, v82, v82 quad_perm:[2,3,0,1] row_mask:0xf bank_mask:0xf bound_ctrl:1
	s_nop 1
	v_add_f32_dpp v82, v82, v82 row_half_mirror row_mask:0xf bank_mask:0xf bound_ctrl:1
	s_nop 1
	v_add_f32_dpp v82, v82, v82 row_mirror row_mask:0xf bank_mask:0xf bound_ctrl:1
	s_nop 0
	v_readlane_b32 s1, v82, 16
	v_readlane_b32 s10, v82, 48
	v_readlane_b32 s4, v82, 0
	v_readlane_b32 s5, v82, 32
	v_mov_b32_e32 v82, s1
	v_mov_b32_e32 v83, s10
	v_pk_add_f32 v[82:83], s[4:5], v[82:83]
	s_nop 0
	v_add_f32_e32 v82, v82, v83
	v_fmamk_f32 v82, v82, 0x3a800000, v220
	v_rsq_f32_e32 v84, v82
	v_lshl_add_u64 v[82:83], s[8:9], 0, v[152:153]
	v_pk_mul_f32 v[76:77], v[76:77], v[84:85] op_sel_hi:[1,0]
	v_pk_mul_f32 v[78:79], v[78:79], v[84:85] op_sel_hi:[1,0]
	v_cndmask_b32_e64 v85, 0, 1, s[2:3]
	v_pk_mul_f32 v[78:79], v[2:3], v[78:79]
	v_cmp_ne_u32_e64 s[4:5], 1, v85
	v_pk_mul_f32 v[76:77], v[0:1], v[76:77]
	s_waitcnt vmcnt(0)
	s_cbranch_vccnz .LBB0_913
	global_store_dwordx4 v[82:83], v[76:79], off
	s_cbranch_execnz .LBB0_869
